# baseline (speedup 1.0000x reference)
; __device__ __forceinline__ int tidx() { int t = threadIdx.x; asm volatile("" : "+v"(t)); return t; }
; __device__ __forceinline__ int bidx() { int t = blockIdx.x; asm volatile("" : "+s"(t)); return t; }
; __device__ __forceinline__ void ln_phase(const h16* V, float* X, h16* Xh, const float* g, const float* b, bool final_out, bool dry = false) {
;   const int tid__ = tidx(); const int lane = tid__ & 63, wid = tid__ >> 6;
;   for (int row = bidx() * 4 + wid; row < T_; row += gridDim.x * 4) {
;     const h16* vr = V + (size_t)row * 1024;
;     f4 v[4];
;     float s = 0.f;
; #pragma unroll
;     for (int i = 0; i < 4; ++i) {
;     ...
; #pragma unroll
;     for (int i = 0; i < 4; ++i) {
;       int c = i * 256 + lane * 4;
;       f4 gg = *(const f4*)(g + c), bb = *(const f4*)(b + c), o;
.LBB0_1506:
	s_or_b64 exec, exec, s[0:1]
	v_readlane_b32 s0, v248, 54
	v_readlane_b32 s8, v248, 62
	v_readlane_b32 s9, v248, 63
	v_readlane_b32 s10, v247, 0
	v_readlane_b32 s11, v247, 1
	v_readlane_b32 s1, v248, 55
	v_readlane_b32 s14, v247, 4
	v_readlane_b32 s15, v247, 5
	v_readlane_b32 s8, v248, 0
	v_readlane_b32 s2, v248, 56
	v_readlane_b32 s3, v248, 57
	s_mov_b64 s[0:1], s[14:15]
	v_readlane_b32 s9, v248, 1
	v_mov_b32_e32 v0, v180
	s_barrier
	v_readlane_b32 s2, v247, 20
	v_ashrrev_i32_e32 v2, 6, v0
	v_readlane_b32 s6, v248, 60
	v_lshl_add_u32 v6, s2, 2, v2
	v_readlane_b32 s7, v248, 61
	v_cmp_gt_i32_e32 vcc, s84, v6
	v_readlane_b32 s4, v248, 58
	v_readlane_b32 s5, v248, 59
	v_readlane_b32 s12, v247, 2
	v_readlane_b32 s13, v247, 3
	v_readlane_b32 s10, v248, 2
	v_readlane_b32 s11, v248, 3
	v_readlane_b32 s3, v247, 21
	v_lshlrev_b32_e32 v18, 4, v180
	ds_write_b128 v18, v[60:63]
	ds_write_b128 v18, v[64:67] offset:4096
	ds_write_b128 v18, v[68:71] offset:8192
	ds_write_b128 v18, v[72:75] offset:12288
	ds_write_b128 v18, v[76:79] offset:16384
	ds_write_b128 v18, v[80:83] offset:20480
	ds_write_b128 v18, v[84:87] offset:24576
	ds_write_b128 v18, v[88:91] offset:28672
	s_and_saveexec_b64 s[6:7], vcc
	s_mov_b32 s2, 0x800000
	s_cbranch_execz .LBB0_1525
	v_lshlrev_b32_e32 v0, 2, v0
	v_and_b32_e32 v8, 0xfc, v0
	v_lshlrev_b32_e32 v0, 1, v8
	v_lshl_add_u64 v[10:11], s[18:19], 0, v[0:1]
	v_and_b32_e32 v0, 64, v230
	v_add_u32_e32 v0, 64, v0
	v_xor_b32_e32 v2, 32, v230
	v_cmp_lt_i32_e32 vcc, v2, v0
	s_add_i32 s88, s16, 0x800
	s_lshl_b64 s[10:11], s[88:89], 2
	v_cndmask_b32_e32 v2, v230, v2, vcc
	v_lshlrev_b32_e32 v9, 2, v2
	v_xor_b32_e32 v2, 16, v230
	v_cmp_lt_i32_e32 vcc, v2, v0
	s_add_u32 s8, s8, s10
	s_addc_u32 s9, s9, s11
	v_cndmask_b32_e32 v2, v230, v2, vcc
	v_lshlrev_b32_e32 v36, 2, v2
	v_xor_b32_e32 v2, 8, v230
	v_cmp_lt_i32_e32 vcc, v2, v0
	s_add_u32 s0, s0, s10
	s_addc_u32 s1, s1, s11
	v_cndmask_b32_e32 v2, v230, v2, vcc
	v_lshlrev_b32_e32 v37, 2, v2
	v_xor_b32_e32 v2, 4, v230
	v_cmp_lt_i32_e32 vcc, v2, v0
	s_mov_b32 s88, 0xfffffc0
	s_nop 0
	v_cndmask_b32_e32 v2, v230, v2, vcc
	v_lshlrev_b32_e32 v38, 2, v2
	v_xor_b32_e32 v2, 2, v230
	v_cmp_lt_i32_e32 vcc, v2, v0
	s_nop 1
	v_cndmask_b32_e32 v2, v230, v2, vcc
	v_lshlrev_b32_e32 v39, 2, v2
	v_xor_b32_e32 v2, 1, v230
	v_cmp_lt_i32_e32 vcc, v2, v0
	s_nop 1
	v_cndmask_b32_e32 v0, v230, v2, vcc
	s_waitcnt vmcnt(2)
	v_lshlrev_b32_e32 v40, 2, v0
	v_lshlrev_b32_e32 v0, 2, v8
	v_lshl_add_u64 v[12:13], s[0:1], 0, v[0:1]
	v_lshl_add_u64 v[14:15], s[8:9], 0, v[0:1]
	global_load_dwordx4 v[60:63], v[12:13], off
	global_load_dwordx4 v[64:67], v[12:13], off offset:1024
	global_load_dwordx4 v[68:71], v[12:13], off offset:2048
	global_load_dwordx4 v[72:75], v[12:13], off offset:3072
	global_load_dwordx4 v[76:79], v[14:15], off
	global_load_dwordx4 v[80:83], v[14:15], off offset:1024
	global_load_dwordx4 v[84:87], v[14:15], off offset:2048
	global_load_dwordx4 v[88:91], v[14:15], off offset:3072
	s_waitcnt vmcnt(0)
	s_mov_b64 s[8:9], 0
	s_branch .LBB0_1509

; __device__ __forceinline__ int bidx() { int t = blockIdx.x; asm volatile("" : "+s"(t)); return t; }
; __device__ __forceinline__ void ln_phase(const h16* V, float* X, h16* Xh, const float* g, const float* b, bool final_out, bool dry = false) {
;     ...
;   for (int row = bidx() * 4 + wid; row < T_; row += gridDim.x * 4) {
;     const h16* vr = V + (size_t)row * 1024;
;     f4 v[4];
;     float s = 0.f;
; #pragma unroll
;     for (int i = 0; i < 4; ++i) {
;       h4 hv = *(const h4*)(vr + i * 256 + lane * 4);
;       v[i][0] = (float)hv[0]; v[i][1] = (float)hv[1]; v[i][2] = (float)hv[2]; v[i][3] = (float)hv[3];
;       s += v[i][0] + v[i][1] + v[i][2] + v[i][3];
;     }
;     for (int o = 32; o > 0; o >>= 1) s += __shfl_xor(s, o);
;     const float mu = s * (1.f / 1024.f);
;     float q = 0.f;
; #pragma unroll
;     for (int i = 0; i < 4; ++i)
; #pragma unroll
;       for (int j = 0; j < 4; ++j) { float d = v[i][j] - mu; q += d * d; }
;     for (int o = 32; o > 0; o >>= 1) q += __shfl_xor(q, o);
;     const float rs = rsqrtf(q * (1.f / 1024.f) + 1e-5f);
;     if (dry && rs != 12345.678f) continue;
; #pragma unroll
;     for (int i = 0; i < 4; ++i) {
;       int c = i * 256 + lane * 4;
;       f4 gg = *(const f4*)(g + c), bb = *(const f4*)(b + c), o;
;       h4 oh;
; #pragma unroll
;       for (int j = 0; j < 4; ++j) { o[j] = (v[i][j] - mu) * rs * gg[j] + bb[j]; oh[j] = (h16)o[j]; }
;       if (final_out) *(f4*)(X + (size_t)row * 1024 + c) = o;
;       else *(h4*)(Xh + (size_t)row * 1024 + c) = oh;
.LBB0_1509:
	v_ashrrev_i32_e32 v7, 31, v6
	v_lshlrev_b64 v[2:3], 11, v[6:7]
	v_lshl_add_u64 v[4:5], v[10:11], 0, v[2:3]
	global_load_dwordx2 v[18:19], v[4:5], off
	global_load_dwordx2 v[16:17], v[4:5], off offset:512
	global_load_dwordx2 v[20:21], v[4:5], off offset:1024
	s_nop 0
	global_load_dwordx2 v[4:5], v[4:5], off offset:1536
	v_readlane_b32 s0, v247, 48
	v_readlane_b32 s1, v247, 49
	s_waitcnt vmcnt(3)
	v_cvt_f32_f16_e32 v44, v18
	s_waitcnt vmcnt(2)
	v_cvt_f32_f16_e32 v28, v16
	v_cvt_f32_f16_sdwa v29, v16 dst_sel:DWORD dst_unused:UNUSED_PAD src0_sel:WORD_1
	v_cvt_f32_f16_sdwa v45, v18 dst_sel:DWORD dst_unused:UNUSED_PAD src0_sel:WORD_1
	v_cvt_f32_f16_e32 v30, v17
	v_cvt_f32_f16_e32 v18, v19
	s_waitcnt vmcnt(0)
	v_cvt_f32_f16_e32 v26, v4
	v_cvt_f32_f16_sdwa v27, v4 dst_sel:DWORD dst_unused:UNUSED_PAD src0_sel:WORD_1
	v_cvt_f32_f16_e32 v22, v20
	v_cvt_f32_f16_sdwa v23, v20 dst_sel:DWORD dst_unused:UNUSED_PAD src0_sel:WORD_1
	v_cvt_f32_f16_sdwa v31, v17 dst_sel:DWORD dst_unused:UNUSED_PAD src0_sel:WORD_1
	v_cvt_f32_f16_sdwa v19, v19 dst_sel:DWORD dst_unused:UNUSED_PAD src0_sel:WORD_1
	v_cvt_f32_f16_e32 v42, v5
	v_cvt_f32_f16_e32 v20, v21
	v_cvt_f32_f16_sdwa v43, v5 dst_sel:DWORD dst_unused:UNUSED_PAD src0_sel:WORD_1
	v_cvt_f32_f16_sdwa v21, v21 dst_sel:DWORD dst_unused:UNUSED_PAD src0_sel:WORD_1
	v_mov_b32_e32 v46, v44
	v_mov_b32_e32 v47, v28
	v_mov_b32_e32 v48, v45
	v_mov_b32_e32 v49, v29
	v_pk_add_f32 v[46:47], v[46:47], v[48:49]
	v_mov_b32_e32 v48, v18
	v_mov_b32_e32 v49, v30
	v_mov_b32_e32 v4, v22
	v_mov_b32_e32 v5, v26
	v_mov_b32_e32 v24, v23
	v_mov_b32_e32 v25, v27
	v_pk_add_f32 v[46:47], v[46:47], v[48:49]
	v_mov_b32_e32 v48, v19
	v_mov_b32_e32 v49, v31
	v_pk_add_f32 v[4:5], v[4:5], v[24:25]
	v_mov_b32_e32 v24, v20
	v_mov_b32_e32 v25, v42
	v_pk_add_f32 v[46:47], v[46:47], v[48:49]
	v_pk_add_f32 v[4:5], v[4:5], v[24:25]
	v_mov_b32_e32 v24, v21
	v_mov_b32_e32 v25, v43
	v_add_f32_e32 v0, 0, v46
	v_pk_add_f32 v[24:25], v[4:5], v[24:25]
	v_add_f32_e32 v0, v0, v47
	v_add_f32_e32 v0, v0, v24
	v_add_f32_e32 v0, v0, v25
	s_nop 1
	v_add_f32_dpp v0, v0, v0 quad_perm:[1,0,3,2] row_mask:0xf bank_mask:0xf bound_ctrl:1
	s_nop 1
	v_add_f32_dpp v0, v0, v0 quad_perm:[2,3,0,1] row_mask:0xf bank_mask:0xf bound_ctrl:1
	s_nop 1
	v_add_f32_dpp v0, v0, v0 row_half_mirror row_mask:0xf bank_mask:0xf bound_ctrl:1
	s_nop 1
	v_add_f32_dpp v0, v0, v0 row_mirror row_mask:0xf bank_mask:0xf bound_ctrl:1
	s_nop 1
	v_readlane_b32 vcc_lo, v0, 0
	v_readlane_b32 vcc_hi, v0, 16
	s_nop 1
	v_mov_b32_e32 v24, vcc_lo
	v_add_f32_e32 v24, vcc_hi, v24
	v_readlane_b32 vcc_lo, v0, 32
	v_readlane_b32 vcc_hi, v0, 48
	s_nop 1
	v_add_f32_e32 v24, vcc_lo, v24
	v_add_f32_e32 v0, vcc_hi, v24
	v_lshl_add_u64 v[16:17], s[0:1], 0, v[2:3]
	s_mov_b64 s[0:1], -1
	v_mul_f32_e32 v0, 0x3a800000, v0
	v_pk_add_f32 v[44:45], v[44:45], v[0:1] op_sel_hi:[1,0] neg_lo:[0,1] neg_hi:[0,1]
	v_pk_add_f32 v[48:49], v[18:19], v[0:1] op_sel_hi:[1,0] neg_lo:[0,1] neg_hi:[0,1]
	v_pk_mul_f32 v[46:47], v[44:45], v[44:45]
	v_pk_mul_f32 v[50:51], v[48:49], v[48:49]
	v_pk_add_f32 v[28:29], v[28:29], v[0:1] op_sel_hi:[1,0] neg_lo:[0,1] neg_hi:[0,1]
	v_pk_add_f32 v[30:31], v[30:31], v[0:1] op_sel_hi:[1,0] neg_lo:[0,1] neg_hi:[0,1]
	v_pk_add_f32 v[22:23], v[22:23], v[0:1] op_sel_hi:[1,0] neg_lo:[0,1] neg_hi:[0,1]
	v_pk_add_f32 v[24:25], v[20:21], v[0:1] op_sel_hi:[1,0] neg_lo:[0,1] neg_hi:[0,1]
	v_pk_add_f32 v[18:19], v[26:27], v[0:1] op_sel_hi:[1,0] neg_lo:[0,1] neg_hi:[0,1]
	v_pk_add_f32 v[20:21], v[42:43], v[0:1] op_sel_hi:[1,0] neg_lo:[0,1] neg_hi:[0,1]
	v_add_f32_e32 v0, v46, v47
	v_add_f32_e32 v0, v50, v0
	v_pk_mul_f32 v[52:53], v[28:29], v[28:29]
	v_add_f32_e32 v0, v51, v0
	v_add_f32_e32 v0, v52, v0
	v_pk_mul_f32 v[54:55], v[30:31], v[30:31]
	v_add_f32_e32 v0, v53, v0
	v_add_f32_e32 v0, v54, v0
	v_pk_mul_f32 v[56:57], v[22:23], v[22:23]
	v_add_f32_e32 v0, v55, v0
	v_add_f32_e32 v0, v56, v0
	v_pk_mul_f32 v[58:59], v[24:25], v[24:25]
	v_add_f32_e32 v0, v57, v0
	v_add_f32_e32 v0, v58, v0
	v_pk_mul_f32 v[26:27], v[18:19], v[18:19]
	v_add_f32_e32 v0, v59, v0
	v_add_f32_e32 v0, v26, v0
	v_pk_mul_f32 v[42:43], v[20:21], v[20:21]
	v_add_f32_e32 v0, v27, v0
	v_add_f32_e32 v0, v42, v0
	v_add_f32_e32 v0, v43, v0
	s_nop 1
	v_add_f32_dpp v0, v0, v0 quad_perm:[1,0,3,2] row_mask:0xf bank_mask:0xf bound_ctrl:1
	s_nop 1
	v_add_f32_dpp v0, v0, v0 quad_perm:[2,3,0,1] row_mask:0xf bank_mask:0xf bound_ctrl:1
	s_nop 1
	v_add_f32_dpp v0, v0, v0 row_half_mirror row_mask:0xf bank_mask:0xf bound_ctrl:1
	s_nop 1
	v_add_f32_dpp v0, v0, v0 row_mirror row_mask:0xf bank_mask:0xf bound_ctrl:1
	s_nop 1
	v_readlane_b32 vcc_lo, v0, 0
	v_readlane_b32 vcc_hi, v0, 16
	s_nop 1
	v_mov_b32_e32 v26, vcc_lo
	v_add_f32_e32 v26, vcc_hi, v26
	v_readlane_b32 vcc_lo, v0, 32
	v_readlane_b32 vcc_hi, v0, 48
	s_nop 1
	v_add_f32_e32 v26, vcc_lo, v26
	v_add_f32_e32 v0, vcc_hi, v26
	v_fmamk_f32 v0, v0, 0x3a800000, v224
	v_cmp_gt_f32_e32 vcc, s2, v0
	v_mul_f32_e32 v26, 0x4b800000, v0
	v_readlane_b32 s2, v247, 42
	v_cndmask_b32_e32 v0, v0, v26, vcc
	v_rsq_f32_e32 v0, v0
	v_readlane_b32 s3, v247, 43
	v_mul_f32_e32 v26, 0x45800000, v0
	v_cndmask_b32_e32 v26, v0, v26, vcc
	v_pk_mul_f32 v[42:43], v[44:45], v[26:27] op_sel_hi:[1,0]
	s_and_b64 vcc, exec, s[2:3]
	v_pk_fma_f32 v[2:3], v[60:61], v[42:43], v[76:77]
	v_pk_mul_f32 v[32:33], v[48:49], v[26:27] op_sel_hi:[1,0]
	s_nop 0
	v_pk_fma_f32 v[4:5], v[62:63], v[32:33], v[78:79]
	v_lshlrev_b32_e32 v32, 1, v8
	s_cbranch_vccz .LBB0_1511
	v_mov_b32_e32 v33, v1
	v_cvt_pk_f16_f32 v35, v4, v5
	v_cvt_pk_f16_f32 v34, v2, v3
	v_lshl_add_u64 v[42:43], v[16:17], 0, v[32:33]
	s_mov_b64 s[0:1], 0
	global_store_dwordx2 v[42:43], v[34:35], off

; __device__ __forceinline__ void ln_phase(const h16* V, float* X, h16* Xh, const float* g, const float* b, bool final_out, bool dry = false) {
;     ...
; #pragma unroll
;     for (int i = 0; i < 4; ++i) {
;       int c = i * 256 + lane * 4;
;       f4 gg = *(const f4*)(g + c), bb = *(const f4*)(b + c), o;
;       h4 oh;
; #pragma unroll
;       for (int j = 0; j < 4; ++j) { o[j] = (v[i][j] - mu) * rs * gg[j] + bb[j]; oh[j] = (h16)o[j]; }
;       if (final_out) *(f4*)(X + (size_t)row * 1024 + c) = o;
;       else *(h4*)(Xh + (size_t)row * 1024 + c) = oh;
.LBB0_1513:
	v_mov_b32_e32 v27, v26
	v_readlane_b32 s2, v247, 42
	v_pk_mul_f32 v[28:29], v[28:29], v[26:27]
	v_readlane_b32 s3, v247, 43
	s_mov_b64 s[0:1], -1
	s_andn2_b64 vcc, exec, s[2:3]
	v_cndmask_b32_e64 v7, 0, 1, s[2:3]
	v_cmp_ne_u32_e64 s[4:5], 1, v7
	v_pk_fma_f32 v[2:3], v[28:29], v[64:65], v[80:81]
	v_pk_mul_f32 v[28:29], v[30:31], v[26:27]
	s_nop 0
	v_pk_fma_f32 v[4:5], v[28:29], v[66:67], v[82:83]
	s_cbranch_vccnz .LBB0_1515
	v_mov_b32_e32 v33, v1
	v_cvt_pk_f16_f32 v29, v4, v5
	v_cvt_pk_f16_f32 v28, v2, v3
	v_lshl_add_u64 v[30:31], v[16:17], 0, v[32:33]
	s_mov_b64 s[0:1], 0
	global_store_dwordx2 v[30:31], v[28:29], off offset:512

; __device__ __forceinline__ void ln_phase(const h16* V, float* X, h16* Xh, const float* g, const float* b, bool final_out, bool dry = false) {
;     ...
; #pragma unroll
;     for (int i = 0; i < 4; ++i) {
;       int c = i * 256 + lane * 4;
;       f4 gg = *(const f4*)(g + c), bb = *(const f4*)(b + c), o;
;       h4 oh;
; #pragma unroll
;       for (int j = 0; j < 4; ++j) { o[j] = (v[i][j] - mu) * rs * gg[j] + bb[j]; oh[j] = (h16)o[j]; }
;       if (final_out) *(f4*)(X + (size_t)row * 1024 + c) = o;
;       else *(h4*)(Xh + (size_t)row * 1024 + c) = oh;
.LBB0_1517:
	v_pk_mul_f32 v[22:23], v[22:23], v[26:27]
	v_pk_mul_f32 v[24:25], v[24:25], v[26:27]
	s_and_b64 vcc, exec, s[4:5]
	s_mov_b64 s[0:1], -1
	v_pk_fma_f32 v[2:3], v[22:23], v[68:69], v[84:85]
	v_pk_fma_f32 v[4:5], v[24:25], v[70:71], v[86:87]
	s_cbranch_vccnz .LBB0_1519
	v_mov_b32_e32 v33, v1
	v_cvt_pk_f16_f32 v23, v4, v5
	v_cvt_pk_f16_f32 v22, v2, v3
	v_lshl_add_u64 v[24:25], v[16:17], 0, v[32:33]
	s_mov_b64 s[0:1], 0
	global_store_dwordx2 v[24:25], v[22:23], off offset:1024

; __device__ __forceinline__ void ln_phase(const h16* V, float* X, h16* Xh, const float* g, const float* b, bool final_out, bool dry = false) {
;     ...
; #pragma unroll
;     for (int i = 0; i < 4; ++i) {
;       int c = i * 256 + lane * 4;
;       f4 gg = *(const f4*)(g + c), bb = *(const f4*)(b + c), o;
;       h4 oh;
; #pragma unroll
;       for (int j = 0; j < 4; ++j) { o[j] = (v[i][j] - mu) * rs * gg[j] + bb[j]; oh[j] = (h16)o[j]; }
;       if (final_out) *(f4*)(X + (size_t)row * 1024 + c) = o;
;       else *(h4*)(Xh + (size_t)row * 1024 + c) = oh;
.LBB0_1521:
	v_pk_mul_f32 v[18:19], v[18:19], v[26:27]
	v_pk_mul_f32 v[20:21], v[20:21], v[26:27]
	s_and_b64 vcc, exec, s[4:5]
	s_mov_b64 s[0:1], -1
	v_pk_fma_f32 v[2:3], v[18:19], v[72:73], v[88:89]
	v_pk_fma_f32 v[4:5], v[20:21], v[74:75], v[90:91]
	s_cbranch_vccnz .LBB0_1523
	v_mov_b32_e32 v33, v1
	v_cvt_pk_f16_f32 v19, v4, v5
	v_cvt_pk_f16_f32 v18, v2, v3
	v_lshl_add_u64 v[16:17], v[16:17], 0, v[32:33]
	s_mov_b64 s[0:1], 0
	global_store_dwordx2 v[16:17], v[18:19], off offset:1536

; __device__ __forceinline__ void ln_phase(const h16* V, float* X, h16* Xh, const float* g, const float* b, bool final_out, bool dry = false) {
;     ...
; #pragma unroll
;     for (int i = 0; i < 4; ++i) {
;       int c = i * 256 + lane * 4;
;       f4 gg = *(const f4*)(g + c), bb = *(const f4*)(b + c), o;
;       h4 oh;
; #pragma unroll
;       for (int j = 0; j < 4; ++j) { o[j] = (v[i][j] - mu) * rs * gg[j] + bb[j]; oh[j] = (h16)o[j]; }
;       if (final_out) *(f4*)(X + (size_t)row * 1024 + c) = o;
;       else *(h4*)(Xh + (size_t)row * 1024 + c) = oh;
;     }
;   }
; }
.LBB0_1525:
	s_or_b64 exec, exec, s[6:7]
	v_lshlrev_b32_e32 v2, 4, v180
	ds_read_b128 v[60:63], v2
	ds_read_b128 v[64:67], v2 offset:4096
	ds_read_b128 v[68:71], v2 offset:8192
	ds_read_b128 v[72:75], v2 offset:12288
	ds_read_b128 v[76:79], v2 offset:16384
	ds_read_b128 v[80:83], v2 offset:20480
	ds_read_b128 v[84:87], v2 offset:24576
	ds_read_b128 v[88:91], v2 offset:28672
	s_waitcnt lgkmcnt(0)
	s_waitcnt vmcnt(0)
	s_barrier
	s_and_saveexec_b64 s[0:1], s[48:49]
	v_readlane_b32 s18, v247, 37
	s_movk_i32 s19, 0x104
	s_cbranch_execnz .LBB0_1526
	s_getpc_b64 s[98:99]
